# attention loop: finishSM VALU of the previous tile interleaved between the 16 qkt MFMAs of each half-step (K fragments moved to idle registers so the streams are independent)
# speedup vs baseline: 1.0069x; 1.0069x over previous
; #define LAS __attribute__((address_space(3)))
; __device__ __forceinline__ void finishSM(f32x16& p0, f32x16& p1, float alpha, float& l_reg, bf16x8& pa0, bf16x8& pa1, bf16x8& pa2, bf16x8& pa3) {
; #pragma unroll
;     for (int r = 0; r < 16; ++r) p1[r] = __builtin_amdgcn_exp2f(p1[r]);
;     float ps = 0;
; #pragma unroll
;     for (int r = 0; r < 16; ++r) ps += p0[r];
; #pragma unroll
;     for (int r = 0; r < 16; ++r) ps += p1[r];
;     { auto rr = __builtin_amdgcn_permlane32_swap(__float_as_uint(ps), __float_as_uint(ps), false, false);
;       ps = __uint_as_float(rr[0]) + __uint_as_float(rr[1]); }
;     l_reg = l_reg * alpha + ps;
;     ...
;     PK4(p0, 0, pa0); PK4(p0, 8, pa1); PK4(p1, 0, pa2); PK4(p1, 8, pa3);
; template <int KB>
; __device__ __forceinline__ void qkt(f32x16& p0, f32x16& p1, lptr K_lds, int r32, int hi, const bf16x8* qr) {
;     p0 = f32x16{}; p1 = f32x16{};
;     lptr kb[4];
; #pragma unroll
;     for (int dd = 0; dd < 4; ++dd) kb[dd] = K_lds + KB * SHM_K + KSWZ(r32, (dd * 16 + hi * 8) * 2);
; #pragma unroll
;     for (int d0 = 0; d0 < 8; ++d0) { lptr a = kb[d0 & 3] + (d0 >> 2) * 128;
;         bf16x8 b0 = *reinterpret_cast<const LAS bf16x8*>(a);
;         bf16x8 b1 = *reinterpret_cast<const LAS bf16x8*>(a + 32 * 256);
;         p0 = __builtin_amdgcn_mfma_f32_32x32x16_bf16(b0, qr[d0], p0, 0, 0, 0);
;         p1 = __builtin_amdgcn_mfma_f32_32x32x16_bf16(b1, qr[d0], p1, 0, 0, 0); }
; }
.LBB0_865:
	ds_read_b128 v[82:85], v187 offset:49152
	ds_read_b128 v[86:89], v187 offset:57344
	ds_read_b128 v[236:239], v185 offset:49152
	ds_read_b128 v[240:243], v185 offset:57344
	s_waitcnt lgkmcnt(3)
	v_mfma_f32_32x32x16_bf16 v[98:113], v[82:85], v[142:145], 0
	v_exp_f32_e32 v80, v80
	v_exp_f32_e32 v1, v1
	v_exp_f32_e32 v78, v78
	s_waitcnt lgkmcnt(2)
	v_mfma_f32_32x32x16_bf16 v[82:97], v[86:89], v[142:145], 0
	v_exp_f32_e32 v79, v79
	v_exp_f32_e32 v76, v76
	v_exp_f32_e32 v77, v77
	s_waitcnt lgkmcnt(0)
	v_mfma_f32_32x32x16_bf16 v[82:97], v[240:243], v[138:141], v[82:97]
	v_exp_f32_e32 v81, v74
	v_exp_f32_e32 v146, v75
	v_exp_f32_e32 v226, v72
	v_mfma_f32_32x32x16_bf16 v[98:113], v[236:239], v[138:141], v[98:113]
	v_exp_f32_e32 v233, v66
	v_add_f32_e32 v66, 0, v160
	v_add_f32_e32 v66, v227, v66
	v_add_f32_e32 v66, v158, v66
	v_add_f32_e32 v66, v161, v66
	ds_read_b128 v[236:239], v184 offset:49152
	ds_read_b128 v[240:243], v184 offset:57344
	s_waitcnt lgkmcnt(0)
	v_mfma_f32_32x32x16_bf16 v[82:97], v[240:243], v[134:137], v[82:97]
	v_add_f32_e32 v66, v157, v66
	v_add_f32_e32 v66, v159, v66
	v_add_f32_e32 v66, v155, v66
	v_add_f32_e32 v66, v156, v66
	v_add_f32_e32 v66, v152, v66
	v_add_f32_e32 v66, v154, v66
	v_mfma_f32_32x32x16_bf16 v[98:113], v[236:239], v[134:137], v[98:113]
	v_add_f32_e32 v66, v151, v66
	v_add_f32_e32 v66, v153, v66
	v_add_f32_e32 v66, v148, v66
	v_add_f32_e32 v66, v150, v66
	v_add_f32_e32 v66, v147, v66
	v_add_f32_e32 v66, v149, v66
	ds_read_b128 v[236:239], v183 offset:49152
	ds_read_b128 v[240:243], v183 offset:57344
	s_waitcnt lgkmcnt(0)
	v_mfma_f32_32x32x16_bf16 v[82:97], v[240:243], v[130:133], v[82:97]
	v_add_f32_e32 v66, v80, v66
	v_add_f32_e32 v66, v1, v66
	v_add_f32_e32 v66, v78, v66
	v_add_f32_e32 v66, v79, v66
	v_add_f32_e32 v66, v76, v66
	v_mfma_f32_32x32x16_bf16 v[98:113], v[236:239], v[130:133], v[98:113]
	v_exp_f32_e32 v228, v73
	v_add_f32_e32 v66, v77, v66
	v_exp_f32_e32 v229, v70
	v_add_f32_e32 v66, v81, v66
	ds_read_b128 v[236:239], v187 offset:49280
	ds_read_b128 v[240:243], v187 offset:57472
	s_waitcnt lgkmcnt(0)
	v_mfma_f32_32x32x16_bf16 v[82:97], v[240:243], v[126:129], v[82:97]
	v_exp_f32_e32 v230, v71
	v_add_f32_e32 v66, v146, v66
	v_exp_f32_e32 v231, v68
	v_add_f32_e32 v66, v226, v66
	v_mfma_f32_32x32x16_bf16 v[98:113], v[236:239], v[126:129], v[98:113]
	v_exp_f32_e32 v232, v69
	v_add_f32_e32 v66, v228, v66
	v_add_f32_e32 v66, v229, v66
	v_exp_f32_e32 v234, v67
	ds_read_b128 v[236:239], v185 offset:49280
	ds_read_b128 v[240:243], v185 offset:57472
	s_waitcnt lgkmcnt(0)
	v_mfma_f32_32x32x16_bf16 v[82:97], v[240:243], v[122:125], v[82:97]
	v_add_f32_e32 v66, v230, v66
	v_add_f32_e32 v66, v231, v66
	v_add_f32_e32 v66, v232, v66
	v_add_f32_e32 v66, v233, v66
	v_add_f32_e32 v224, v234, v66
	v_mov_b32_e32 v225, v224
	v_mfma_f32_32x32x16_bf16 v[98:113], v[236:239], v[122:125], v[98:113]
	v_cvt_pk_bf16_f32 v66, v160, v227
	v_cvt_pk_bf16_f32 v67, v158, v161
	v_cvt_pk_bf16_f32 v68, v157, v159
	v_cvt_pk_bf16_f32 v69, v155, v156
	v_cvt_pk_bf16_f32 v70, v152, v154
	v_cvt_pk_bf16_f32 v71, v151, v153
	ds_read_b128 v[236:239], v184 offset:49280
	ds_read_b128 v[240:243], v184 offset:57472
	s_waitcnt lgkmcnt(0)
	v_mfma_f32_32x32x16_bf16 v[82:97], v[240:243], v[118:121], v[82:97]
	v_cvt_pk_bf16_f32 v72, v148, v150
	v_cvt_pk_bf16_f32 v73, v147, v149
	v_cvt_pk_bf16_f32 v74, v80, v1
	v_cvt_pk_bf16_f32 v75, v78, v79
	v_cvt_pk_bf16_f32 v76, v76, v77
	v_cvt_pk_bf16_f32 v77, v81, v146
	v_mfma_f32_32x32x16_bf16 v[98:113], v[236:239], v[118:121], v[98:113]
	v_cvt_pk_bf16_f32 v78, v226, v228
	v_cvt_pk_bf16_f32 v79, v229, v230
	v_cvt_pk_bf16_f32 v80, v231, v232
	v_cvt_pk_bf16_f32 v81, v233, v234
	s_nop 1
	v_permlane32_swap_b32_e32 v224, v225
	ds_read_b128 v[236:239], v183 offset:49280
	ds_read_b128 v[240:243], v183 offset:57472
	s_waitcnt lgkmcnt(0)
	v_mfma_f32_32x32x16_bf16 v[82:97], v[240:243], v[114:117], v[82:97]
	v_permlane32_swap_b32_e32 v66, v68
	v_permlane32_swap_b32_e32 v67, v69
	v_permlane32_swap_b32_e32 v70, v72
	v_permlane32_swap_b32_e32 v71, v73
	v_permlane32_swap_b32_e32 v74, v76
	v_permlane32_swap_b32_e32 v75, v77
	v_mfma_f32_32x32x16_bf16 v[98:113], v[236:239], v[114:117], v[98:113]
	v_permlane32_swap_b32_e32 v78, v80
	v_permlane32_swap_b32_e32 v79, v81
	v_add_u32_e32 v227, s89, v186
	v_add_u32_e32 v146, 1, v227
	v_add_u32_e32 v148, 33, v227
	v_ashrrev_i32_e32 v147, 31, v146
	v_ashrrev_i32_e32 v149, 31, v148
	v_lshlrev_b64 v[154:155], 8, v[146:147]
	v_lshlrev_b64 v[156:157], 8, v[148:149]
	v_lshl_add_u64 v[146:147], v[176:177], 0, v[154:155]
	v_lshl_add_u64 v[150:151], v[176:177], 0, v[156:157]
	v_lshl_add_u64 v[154:155], v[178:179], 0, v[154:155]
	v_lshl_add_u64 v[158:159], v[178:179], 0, v[156:157]
	global_load_dwordx4 v[146:149], v[146:147], off
	s_nop 0
	global_load_dwordx4 v[150:153], v[150:151], off
	s_nop 0
	global_load_dwordx4 v[154:157], v[154:155], off
	s_nop 0
	global_load_dwordx4 v[158:161], v[158:159], off
	ds_read_b64_tr_b16 v[228:229], v181 offset:0
	ds_read_b64_tr_b16 v[230:231], v181 offset:0x800
	ds_read_b64_tr_b16 v[232:233], v181 offset:0x1000
	ds_read_b64_tr_b16 v[234:235], v181 offset:0x1800
	ds_read_b64_tr_b16 v[236:237], v181 offset:0x2000
	ds_read_b64_tr_b16 v[238:239], v181 offset:0x2800
	ds_read_b64_tr_b16 v[240:241], v181 offset:0x3000
	ds_read_b64_tr_b16 v[242:243], v181 offset:0x3800
	s_waitcnt lgkmcnt(0)
; #define LAS __attribute__((address_space(3)))
; __device__ __forceinline__ void bias_tile(f32x16& p0, f32x16& p1, const LAS float* cs) {
; #pragma unroll
;     for (int i = 0; i < 4; ++i) { const f32x4 a = *(const LAS f32x4*)(cs + 8 * i), b = *(const LAS f32x4*)(cs + 32 + 8 * i);
; #pragma unroll
;         for (int j = 0; j < 4; ++j) { p0[4 * i + j] = fmaf(p0[4 * i + j], C2, a[j]); p1[4 * i + j] = fmaf(p1[4 * i + j], C2, b[j]); } }
; }
; template <int VB>
; __device__ __forceinline__ void pv_tile(f32x16* o, int vb0, bf16x8 pa0, bf16x8 pa1, bf16x8 pa2, bf16x8 pa3) {
;     ...
;     PV_D0(0); PV_D0(1); PV_D0(2); PV_D0(3);
;     ...
; }
	s_nop 0
	v_mfma_f32_32x32x16_bf16 v[50:65], v[66:69], v[228:231], v[50:65]
	ds_read_b64_tr_b16 v[228:229], v181 offset:0x200
	ds_read_b64_tr_b16 v[230:231], v181 offset:0xa00
	v_mfma_f32_32x32x16_bf16 v[50:65], v[70:73], v[232:235], v[50:65]
	ds_read_b64_tr_b16 v[232:233], v181 offset:0x1200
	ds_read_b64_tr_b16 v[234:235], v181 offset:0x1a00
	v_mfma_f32_32x32x16_bf16 v[50:65], v[74:77], v[236:239], v[50:65]
	ds_read_b64_tr_b16 v[236:237], v181 offset:0x2200
	ds_read_b64_tr_b16 v[238:239], v181 offset:0x2a00
	v_mfma_f32_32x32x16_bf16 v[50:65], v[78:81], v[240:243], v[50:65]
	ds_read_b64_tr_b16 v[240:241], v181 offset:0x3200
	ds_read_b64_tr_b16 v[242:243], v181 offset:0x3a00
	s_waitcnt lgkmcnt(0)
	v_mfma_f32_32x32x16_bf16 v[34:49], v[66:69], v[228:231], v[34:49]
	ds_read_b64_tr_b16 v[228:229], v181 offset:0x400
	ds_read_b64_tr_b16 v[230:231], v181 offset:0xc00
	v_mfma_f32_32x32x16_bf16 v[34:49], v[70:73], v[232:235], v[34:49]
	ds_read_b64_tr_b16 v[232:233], v181 offset:0x1400
	ds_read_b64_tr_b16 v[234:235], v181 offset:0x1c00
	v_mfma_f32_32x32x16_bf16 v[34:49], v[74:77], v[236:239], v[34:49]
	ds_read_b64_tr_b16 v[236:237], v181 offset:0x2400
	ds_read_b64_tr_b16 v[238:239], v181 offset:0x2c00
	v_mfma_f32_32x32x16_bf16 v[34:49], v[78:81], v[240:243], v[34:49]
	ds_read_b64_tr_b16 v[240:241], v181 offset:0x3400
	ds_read_b64_tr_b16 v[242:243], v181 offset:0x3c00
	s_waitcnt lgkmcnt(0)
	v_mfma_f32_32x32x16_bf16 v[18:33], v[66:69], v[228:231], v[18:33]
	ds_read_b64_tr_b16 v[228:229], v181 offset:0x600
	ds_read_b64_tr_b16 v[230:231], v181 offset:0xe00
	v_mfma_f32_32x32x16_bf16 v[18:33], v[70:73], v[232:235], v[18:33]
	ds_read_b64_tr_b16 v[232:233], v181 offset:0x1600
	ds_read_b64_tr_b16 v[234:235], v181 offset:0x1e00
	v_mfma_f32_32x32x16_bf16 v[18:33], v[74:77], v[236:239], v[18:33]
	ds_read_b64_tr_b16 v[236:237], v181 offset:0x2600
	ds_read_b64_tr_b16 v[238:239], v181 offset:0x2e00
	v_mfma_f32_32x32x16_bf16 v[18:33], v[78:81], v[240:243], v[18:33]
	ds_read_b64_tr_b16 v[240:241], v181 offset:0x3600
	ds_read_b64_tr_b16 v[242:243], v181 offset:0x3e00
	s_waitcnt lgkmcnt(0)
	v_mfma_f32_32x32x16_bf16 v[2:17], v[66:69], v[228:231], v[2:17]
	s_cmp_le_i32 s89, s80
	v_mfma_f32_32x32x16_bf16 v[2:17], v[70:73], v[232:235], v[2:17]
	v_mfma_f32_32x32x16_bf16 v[2:17], v[74:77], v[236:239], v[2:17]
	v_mfma_f32_32x32x16_bf16 v[2:17], v[78:81], v[240:243], v[2:17]
	ds_read_b128 v[228:231], v223 offset:128
	ds_read_b128 v[78:81], v223
	ds_read_b128 v[70:73], v223 offset:32
	ds_read_b128 v[232:235], v223 offset:160
	ds_read_b128 v[74:77], v223 offset:64
	ds_read_b128 v[236:239], v223 offset:192
	ds_read_b128 v[240:243], v223 offset:96
	ds_read_b128 v[244:247], v223 offset:224
	s_waitcnt lgkmcnt(6)
	v_pk_fma_f32 v[100:101], v[100:101], s[2:3], v[80:81] op_sel_hi:[1,0,1]
	s_waitcnt lgkmcnt(3)
	v_pk_fma_f32 v[68:69], v[106:107], s[2:3], v[74:75] op_sel_hi:[1,0,1]
	v_pk_fma_f32 v[74:75], v[102:103], s[2:3], v[70:71] op_sel_hi:[1,0,1]
	s_waitcnt lgkmcnt(1)
	v_pk_fma_f32 v[66:67], v[110:111], s[2:3], v[240:241] op_sel_hi:[1,0,1]
	v_pk_fma_f32 v[70:71], v[112:113], s[2:3], v[242:243] op_sel_hi:[1,0,1]
	v_pk_fma_f32 v[76:77], v[108:109], s[2:3], v[76:77] op_sel_hi:[1,0,1]
	v_pk_fma_f32 v[102:103], v[104:105], s[2:3], v[72:73] op_sel_hi:[1,0,1]
	v_pk_fma_f32 v[98:99], v[98:99], s[2:3], v[78:79] op_sel_hi:[1,0,1]
	s_waitcnt lgkmcnt(0)
	v_pk_fma_f32 v[72:73], v[94:95], s[2:3], v[244:245] op_sel_hi:[1,0,1]
	v_pk_fma_f32 v[78:79], v[90:91], s[2:3], v[236:237] op_sel_hi:[1,0,1]
	v_pk_fma_f32 v[86:87], v[86:87], s[2:3], v[232:233] op_sel_hi:[1,0,1]
	v_pk_fma_f32 v[80:81], v[96:97], s[2:3], v[246:247] op_sel_hi:[1,0,1]
	v_pk_fma_f32 v[90:91], v[92:93], s[2:3], v[238:239] op_sel_hi:[1,0,1]
	v_pk_fma_f32 v[88:89], v[88:89], s[2:3], v[234:235] op_sel_hi:[1,0,1]
	v_pk_fma_f32 v[84:85], v[84:85], s[2:3], v[230:231] op_sel_hi:[1,0,1]
	v_pk_fma_f32 v[82:83], v[82:83], s[2:3], v[228:229] op_sel_hi:[1,0,1]
	s_cbranch_scc1 .LBB0_867
; __device__ __forceinline__ void mask_tile(f32x16& p0, f32x16& p1, int dq) {
;     const float NEG = -__builtin_inff();
; #pragma unroll
;     for (int r = 0; r < 16; ++r) { const int c = (r & 3) + 8 * (r >> 2);
;         if (dq - c < 0) p0[r] = NEG;
;         if (dq - c - 32 < 0) p1[r] = NEG; }
; }
	v_add_u32_e32 v1, 64, v222
	v_cmp_gt_i32_e64 s[70:71], 26, v1
	v_cmp_gt_i32_e64 s[72:73], 27, v1
	v_cmp_gt_i32_e64 s[68:69], 25, v1
	s_and_b64 s[70:71], s[72:73], s[70:71]
	v_cmp_gt_i32_e64 s[66:67], 24, v1
	s_and_b64 s[68:69], s[70:71], s[68:69]
	v_cmp_gt_i32_e64 s[64:65], 19, v1
	s_and_b64 s[66:67], s[68:69], s[66:67]
	v_cmp_gt_i32_e64 s[62:63], 18, v1
	s_and_b64 s[64:65], s[66:67], s[64:65]
	v_cmp_gt_i32_e64 s[60:61], 17, v1
	s_and_b64 s[62:63], s[64:65], s[62:63]
	v_cmp_gt_i32_e64 s[58:59], 16, v1
	s_and_b64 s[60:61], s[62:63], s[60:61]
	v_cmp_gt_i32_e64 s[56:57], 11, v1
	s_and_b64 s[58:59], s[60:61], s[58:59]
	v_cmp_gt_i32_e64 s[54:55], 10, v1
	s_and_b64 s[56:57], s[58:59], s[56:57]
	v_cmp_gt_i32_e64 s[52:53], 9, v1
	s_and_b64 s[54:55], s[56:57], s[54:55]
	v_cmp_gt_i32_e64 s[50:51], 8, v1
	s_and_b64 s[52:53], s[54:55], s[52:53]
	v_cmp_gt_i32_e64 s[48:49], 3, v1
	s_and_b64 s[50:51], s[52:53], s[50:51]
	v_cmp_gt_i32_e64 s[46:47], 2, v1
	s_and_b64 s[48:49], s[50:51], s[48:49]
	v_cmp_gt_i32_e64 s[44:45], 1, v1
	s_and_b64 s[46:47], s[48:49], s[46:47]
	v_cmp_gt_i32_e64 s[42:43], 0, v1
	s_and_b64 s[44:45], s[46:47], s[44:45]
	s_and_b64 s[42:43], s[44:45], s[42:43]
	v_cmp_gt_i32_e64 s[38:39], 58, v1
	v_cndmask_b32_e64 v98, v98, v206, s[42:43]
	v_cmp_gt_i32_e64 s[42:43], 59, v1
	v_cmp_gt_i32_e64 s[36:37], 57, v1
	s_and_b64 s[38:39], s[42:43], s[38:39]
	v_cmp_gt_i32_e64 s[34:35], 56, v1
	s_and_b64 s[36:37], s[38:39], s[36:37]
	v_cmp_gt_i32_e64 s[30:31], 51, v1
	s_and_b64 s[34:35], s[36:37], s[34:35]
	v_cmp_gt_i32_e64 s[28:29], 50, v1
	s_and_b64 s[30:31], s[34:35], s[30:31]
	v_cmp_gt_i32_e64 s[26:27], 49, v1
	s_and_b64 s[28:29], s[30:31], s[28:29]
	v_cmp_gt_i32_e64 s[24:25], 48, v1
	s_and_b64 s[26:27], s[28:29], s[26:27]
	v_cmp_gt_i32_e64 s[22:23], 43, v1
	s_and_b64 s[24:25], s[26:27], s[24:25]
	v_cmp_gt_i32_e64 s[20:21], 42, v1
	s_and_b64 s[22:23], s[24:25], s[22:23]
	v_cmp_gt_i32_e64 s[18:19], 41, v1
	s_and_b64 s[20:21], s[22:23], s[20:21]
	v_cmp_gt_i32_e64 s[16:17], 40, v1
	s_and_b64 s[18:19], s[20:21], s[18:19]
	v_cmp_gt_i32_e64 s[14:15], 35, v1
	s_and_b64 s[16:17], s[18:19], s[16:17]
	v_cmp_gt_i32_e64 s[12:13], 34, v1
	s_and_b64 s[14:15], s[16:17], s[14:15]
	v_cmp_gt_i32_e64 s[10:11], 33, v1
	s_and_b64 s[12:13], s[14:15], s[12:13]
	v_cmp_gt_i32_e32 vcc, 32, v1
	s_and_b64 s[10:11], s[12:13], s[10:11]
	s_and_b64 vcc, s[10:11], vcc
	v_cndmask_b32_e64 v71, v71, v206, s[72:73]
	v_cndmask_b32_e64 v70, v70, v206, s[70:71]
	v_cndmask_b32_e64 v67, v67, v206, s[68:69]
	v_cndmask_b32_e64 v66, v66, v206, s[66:67]
	v_cndmask_b32_e64 v77, v77, v206, s[64:65]
	v_cndmask_b32_e64 v76, v76, v206, s[62:63]
	v_cndmask_b32_e64 v69, v69, v206, s[60:61]
	v_cndmask_b32_e64 v68, v68, v206, s[58:59]
	v_cndmask_b32_e64 v103, v103, v206, s[56:57]
	v_cndmask_b32_e64 v102, v102, v206, s[54:55]
	v_cndmask_b32_e64 v75, v75, v206, s[52:53]
	v_cndmask_b32_e64 v74, v74, v206, s[50:51]
	v_cndmask_b32_e64 v101, v101, v206, s[48:49]
	v_cndmask_b32_e64 v100, v100, v206, s[46:47]
	v_cndmask_b32_e64 v99, v99, v206, s[44:45]
	v_cndmask_b32_e64 v81, v81, v206, s[42:43]
	v_cndmask_b32_e64 v80, v80, v206, s[38:39]
	v_cndmask_b32_e64 v73, v73, v206, s[36:37]
	v_cndmask_b32_e64 v72, v72, v206, s[34:35]
	v_cndmask_b32_e64 v91, v91, v206, s[30:31]
	v_cndmask_b32_e64 v90, v90, v206, s[28:29]
	v_cndmask_b32_e64 v79, v79, v206, s[26:27]
	v_cndmask_b32_e64 v78, v78, v206, s[24:25]
	v_cndmask_b32_e64 v89, v89, v206, s[22:23]
	v_cndmask_b32_e64 v88, v88, v206, s[20:21]
	v_cndmask_b32_e64 v87, v87, v206, s[18:19]
	v_cndmask_b32_e64 v86, v86, v206, s[16:17]
	v_cndmask_b32_e64 v85, v85, v206, s[14:15]
	v_cndmask_b32_e64 v84, v84, v206, s[12:13]
	v_cndmask_b32_e64 v83, v83, v206, s[10:11]
	v_cndmask_b32_e32 v82, v82, v206, vcc

; #define LAS __attribute__((address_space(3)))
; __device__ __forceinline__ void partialSM(f32x16& p0, f32x16& p1, float& m_reg, float& alpha) {
;     float pmax = p0[0];
; #pragma unroll
;     for (int r = 1; r < 16; ++r) pmax = fmaxf(pmax, p0[r]);
; #pragma unroll
;     for (int r = 0; r < 16; ++r) pmax = fmaxf(pmax, p1[r]);
;     { auto rr = __builtin_amdgcn_permlane32_swap(__float_as_uint(pmax), __float_as_uint(pmax), false, false);
;       pmax = fmaxf(__uint_as_float(rr[0]), __uint_as_float(rr[1])); }
;     float mn;
;     if (__builtin_expect(__all(pmax - m_reg <= THR2), 1)) { mn = m_reg; alpha = 1.f; }
;     else { mn = fmaxf(m_reg, pmax); alpha = __builtin_amdgcn_exp2f(m_reg - mn); m_reg = mn; }
; #pragma unroll
;     for (int r = 0; r < 16; ++r) p0[r] = p0[r] - mn;
; #pragma unroll
;     for (int r = 0; r < 16; ++r) p1[r] = p1[r] - mn;
; #pragma unroll
;     for (int r = 0; r < 16; ++r) p0[r] = __builtin_amdgcn_exp2f(p0[r]);
; }
; __device__ __forceinline__ void finishSM(f32x16& p0, f32x16& p1, float alpha, float& l_reg, bf16x8& pa0, bf16x8& pa1, bf16x8& pa2, bf16x8& pa3) {
; #pragma unroll
;     for (int r = 0; r < 16; ++r) p1[r] = __builtin_amdgcn_exp2f(p1[r]);
;     float ps = 0;
; #pragma unroll
;     for (int r = 0; r < 16; ++r) ps += p0[r];
; #pragma unroll
;     for (int r = 0; r < 16; ++r) ps += p1[r];
;     { auto rr = __builtin_amdgcn_permlane32_swap(__float_as_uint(ps), __float_as_uint(ps), false, false);
;       ps = __uint_as_float(rr[0]) + __uint_as_float(rr[1]); }
;     l_reg = l_reg * alpha + ps;
;     ...
;     PK4(p0, 0, pa0); PK4(p0, 8, pa1); PK4(p1, 0, pa2); PK4(p1, 8, pa3);
; template <int KB>
; __device__ __forceinline__ void qkt(f32x16& p0, f32x16& p1, lptr K_lds, int r32, int hi, const bf16x8* qr) {
;     p0 = f32x16{}; p1 = f32x16{};
;     lptr kb[4];
; #pragma unroll
;     for (int dd = 0; dd < 4; ++dd) kb[dd] = K_lds + KB * SHM_K + KSWZ(r32, (dd * 16 + hi * 8) * 2);
; #pragma unroll
;     for (int d0 = 0; d0 < 8; ++d0) { lptr a = kb[d0 & 3] + (d0 >> 2) * 128;
;         bf16x8 b0 = *reinterpret_cast<const LAS bf16x8*>(a);
;         bf16x8 b1 = *reinterpret_cast<const LAS bf16x8*>(a + 32 * 256);
;         p0 = __builtin_amdgcn_mfma_f32_32x32x16_bf16(b0, qr[d0], p0, 0, 0, 0);
;         p1 = __builtin_amdgcn_mfma_f32_32x32x16_bf16(b1, qr[d0], p1, 0, 0, 0); }
; }
.LBB0_871:
	v_cndmask_b32_e64 v1, v1, v220, s[10:11]
	v_sub_f32_e32 v92, v98, v1
	v_sub_f32_e32 v93, v99, v1
	v_sub_f32_e32 v94, v100, v1
	v_sub_f32_e32 v95, v101, v1
	v_sub_f32_e32 v74, v74, v1
	v_sub_f32_e32 v75, v75, v1
	v_sub_f32_e32 v96, v102, v1
	v_sub_f32_e32 v97, v103, v1
	v_sub_f32_e32 v68, v68, v1
	v_sub_f32_e32 v69, v69, v1
	v_sub_f32_e32 v76, v76, v1
	v_sub_f32_e32 v77, v77, v1
	v_sub_f32_e32 v66, v66, v1
	v_sub_f32_e32 v67, v67, v1
	v_sub_f32_e32 v70, v70, v1
	v_sub_f32_e32 v71, v71, v1
	v_exp_f32_e32 v98, v92
	v_exp_f32_e32 v113, v93
	v_exp_f32_e32 v99, v94
	v_exp_f32_e32 v112, v95
	v_exp_f32_e32 v100, v74
	v_exp_f32_e32 v111, v75
	v_exp_f32_e32 v101, v96
	v_exp_f32_e32 v110, v97
	v_exp_f32_e32 v102, v68
	v_exp_f32_e32 v109, v69
	v_exp_f32_e32 v103, v76
	v_exp_f32_e32 v108, v77
	v_exp_f32_e32 v104, v66
	v_exp_f32_e32 v107, v67
	v_exp_f32_e32 v105, v70
	v_exp_f32_e32 v106, v71
	v_sub_f32_e32 v220, v82, v1
	v_sub_f32_e32 v236, v83, v1
	v_sub_f32_e32 v237, v84, v1
	v_sub_f32_e32 v238, v85, v1
	v_sub_f32_e32 v239, v86, v1
	v_sub_f32_e32 v240, v87, v1
	v_sub_f32_e32 v241, v88, v1
	v_sub_f32_e32 v242, v89, v1
	v_sub_f32_e32 v243, v78, v1
	v_sub_f32_e32 v244, v79, v1
	v_sub_f32_e32 v245, v90, v1
	v_sub_f32_e32 v246, v91, v1
	v_sub_f32_e32 v247, v72, v1
	v_sub_f32_e32 v248, v73, v1
	v_sub_f32_e32 v249, v80, v1
	v_sub_f32_e32 v250, v81, v1
	s_waitcnt lgkmcnt(0)
	s_barrier
	ds_read_b128 v[66:69], v187 offset:32768
	ds_read_b128 v[70:73], v187 offset:40960
	ds_read_b128 v[146:149], v185 offset:32768
	ds_read_b128 v[150:153], v185 offset:40960
	s_waitcnt lgkmcnt(3)
	v_mfma_f32_32x32x16_bf16 v[82:97], v[66:69], v[142:145], 0
	v_exp_f32_e32 v220, v220
	v_add_f32_e32 v228, 0, v98
	v_add_f32_e32 v228, v113, v228
	v_add_f32_e32 v228, v99, v228
	v_add_f32_e32 v228, v112, v228
	s_waitcnt lgkmcnt(2)
	v_mfma_f32_32x32x16_bf16 v[66:81], v[70:73], v[142:145], 0
	v_add_f32_e32 v228, v100, v228
	v_add_f32_e32 v228, v111, v228
	v_add_f32_e32 v228, v101, v228
	v_add_f32_e32 v228, v110, v228
	v_add_f32_e32 v228, v102, v228
	v_add_f32_e32 v228, v109, v228
	s_waitcnt lgkmcnt(1)
	v_mfma_f32_32x32x16_bf16 v[82:97], v[146:149], v[138:141], v[82:97]
	v_add_f32_e32 v228, v103, v228
	v_add_f32_e32 v228, v108, v228
	v_add_f32_e32 v228, v104, v228
	v_exp_f32_e32 v230, v236
	v_add_f32_e32 v228, v107, v228
	s_waitcnt lgkmcnt(0)
	v_mfma_f32_32x32x16_bf16 v[66:81], v[150:153], v[138:141], v[66:81]
	v_exp_f32_e32 v231, v237
	v_add_f32_e32 v228, v105, v228
	v_exp_f32_e32 v232, v238
	v_add_f32_e32 v228, v106, v228
	ds_read_b128 v[146:149], v184 offset:32768
	ds_read_b128 v[150:153], v184 offset:40960
	s_waitcnt lgkmcnt(1)
	v_mfma_f32_32x32x16_bf16 v[82:97], v[146:149], v[134:137], v[82:97]
	v_exp_f32_e32 v233, v239
	v_add_f32_e32 v228, v220, v228
	v_exp_f32_e32 v234, v240
	v_add_f32_e32 v228, v230, v228
	s_waitcnt lgkmcnt(0)
	v_mfma_f32_32x32x16_bf16 v[66:81], v[150:153], v[134:137], v[66:81]
	v_exp_f32_e32 v235, v241
	v_add_f32_e32 v228, v231, v228
	v_exp_f32_e32 v236, v242
	v_add_f32_e32 v228, v232, v228
	ds_read_b128 v[146:149], v183 offset:32768
	ds_read_b128 v[150:153], v183 offset:40960
	s_waitcnt lgkmcnt(1)
	v_mfma_f32_32x32x16_bf16 v[82:97], v[146:149], v[130:133], v[82:97]
	v_exp_f32_e32 v237, v243
	v_add_f32_e32 v228, v233, v228
	v_exp_f32_e32 v238, v244
	v_add_f32_e32 v228, v234, v228
	s_waitcnt lgkmcnt(0)
	v_mfma_f32_32x32x16_bf16 v[66:81], v[150:153], v[130:133], v[66:81]
	v_exp_f32_e32 v239, v245
	v_add_f32_e32 v228, v235, v228
	v_exp_f32_e32 v240, v246
	v_add_f32_e32 v228, v236, v228
	ds_read_b128 v[146:149], v187 offset:32896
	ds_read_b128 v[150:153], v187 offset:41088
	s_waitcnt lgkmcnt(1)
	v_mfma_f32_32x32x16_bf16 v[82:97], v[146:149], v[126:129], v[82:97]
	v_exp_f32_e32 v241, v247
	v_add_f32_e32 v228, v237, v228
	v_exp_f32_e32 v242, v248
	v_add_f32_e32 v228, v238, v228
	s_waitcnt lgkmcnt(0)
	v_mfma_f32_32x32x16_bf16 v[66:81], v[150:153], v[126:129], v[66:81]
	v_exp_f32_e32 v243, v249
	v_add_f32_e32 v228, v239, v228
	v_exp_f32_e32 v244, v250
	v_add_f32_e32 v228, v240, v228
	ds_read_b128 v[146:149], v185 offset:32896
	ds_read_b128 v[150:153], v185 offset:41088
	s_waitcnt lgkmcnt(1)
	v_mfma_f32_32x32x16_bf16 v[82:97], v[146:149], v[122:125], v[82:97]
	v_add_f32_e32 v228, v241, v228
	v_add_f32_e32 v228, v242, v228
	v_add_f32_e32 v228, v243, v228
	v_add_f32_e32 v228, v244, v228
	v_mov_b32_e32 v229, v228
	v_cvt_pk_bf16_f32 v98, v98, v113
	s_waitcnt lgkmcnt(0)
	v_mfma_f32_32x32x16_bf16 v[66:81], v[150:153], v[122:125], v[66:81]
	v_cvt_pk_bf16_f32 v99, v99, v112
	v_cvt_pk_bf16_f32 v100, v100, v111
	v_cvt_pk_bf16_f32 v101, v101, v110
	v_cvt_pk_bf16_f32 v102, v102, v109
	v_cvt_pk_bf16_f32 v103, v103, v108
	v_cvt_pk_bf16_f32 v104, v104, v107
	ds_read_b128 v[146:149], v184 offset:32896
	ds_read_b128 v[150:153], v184 offset:41088
	s_waitcnt lgkmcnt(1)
	v_mfma_f32_32x32x16_bf16 v[82:97], v[146:149], v[118:121], v[82:97]
	v_cvt_pk_bf16_f32 v105, v105, v106
	v_cvt_pk_bf16_f32 v106, v220, v230
	v_cvt_pk_bf16_f32 v107, v231, v232
	v_cvt_pk_bf16_f32 v108, v233, v234
	v_cvt_pk_bf16_f32 v109, v235, v236
	v_cvt_pk_bf16_f32 v110, v237, v238
	s_waitcnt lgkmcnt(0)
	v_mfma_f32_32x32x16_bf16 v[66:81], v[150:153], v[118:121], v[66:81]
	v_cvt_pk_bf16_f32 v111, v239, v240
	v_cvt_pk_bf16_f32 v112, v241, v242
	v_cvt_pk_bf16_f32 v113, v243, v244
	s_nop 1
	v_permlane32_swap_b32_e32 v228, v229
	v_permlane32_swap_b32_e32 v98, v100
	ds_read_b128 v[146:149], v183 offset:32896
	ds_read_b128 v[150:153], v183 offset:41088
	s_waitcnt lgkmcnt(1)
	v_mfma_f32_32x32x16_bf16 v[82:97], v[146:149], v[114:117], v[82:97]
	v_permlane32_swap_b32_e32 v99, v101
	v_permlane32_swap_b32_e32 v102, v104
	v_permlane32_swap_b32_e32 v103, v105
	v_permlane32_swap_b32_e32 v106, v108
	v_permlane32_swap_b32_e32 v107, v109
	v_permlane32_swap_b32_e32 v110, v112
	s_waitcnt lgkmcnt(0)
	v_mfma_f32_32x32x16_bf16 v[66:81], v[150:153], v[114:117], v[66:81]
	v_permlane32_swap_b32_e32 v111, v113
	s_add_i32 s10, s88, 1
	s_cmp_lt_i32 s10, s81
	s_cselect_b64 s[40:41], -1, 0
	s_cmp_ge_i32 s10, s81
	s_cbranch_scc1 .LBB0_873
	v_add_u32_e32 v146, 0x41, v227
	v_add_u32_e32 v148, 0x61, v227
	v_ashrrev_i32_e32 v147, 31, v146
	v_ashrrev_i32_e32 v149, 31, v148
	v_lshlrev_b64 v[154:155], 8, v[146:147]
	v_lshlrev_b64 v[156:157], 8, v[148:149]
	v_lshl_add_u64 v[146:147], v[176:177], 0, v[154:155]
	v_lshl_add_u64 v[150:151], v[176:177], 0, v[156:157]
	v_lshl_add_u64 v[154:155], v[178:179], 0, v[154:155]
	v_lshl_add_u64 v[158:159], v[178:179], 0, v[156:157]
	global_load_dwordx4 v[146:149], v[146:147], off
	s_nop 0
	global_load_dwordx4 v[150:153], v[150:151], off
	s_nop 0
	global_load_dwordx4 v[154:157], v[154:155], off
	s_nop 0
	global_load_dwordx4 v[158:161], v[158:159], off
